# v207 + last unit's unused trailing K-tile re-loads in P2/P4/P9 point at the just-consumed (L2-hot) tile pair
# baseline (speedup 1.0000x reference)
.LBB0_124:
	s_ashr_i32 s29, s28, 31
	s_lshl_b64 s[8:9], s[28:29], 19
	s_add_u32 s30, s16, s8
	s_addc_u32 s31, s79, s9
	s_and_b64 s[8:9], s[2:3], exec
	ds_read_b128 v[2:5], v141
	ds_read_b128 v[6:9], v141 offset:1024
	ds_read_b128 v[10:13], v141 offset:2048
	ds_read_b128 v[14:17], v141 offset:3072
	ds_read_b128 v[18:21], v142
	ds_read_b128 v[22:25], v142 offset:1024
	ds_read_b128 v[26:29], v142 offset:2048
	ds_read_b128 v[30:33], v142 offset:3072
	s_cselect_b32 s29, s31, s73
	s_cselect_b32 s93, s30, s72
	s_cselect_b32 s8, 0, 0x700
	s_add_u32 s93, s93, s8
	s_addc_u32 s29, s29, 0
	s_ashr_i32 s21, s20, 31
	s_lshl_b64 s[8:9], s[20:21], 19
	s_add_u32 s64, s17, s8
	s_addc_u32 s65, s19, s9
	s_and_b64 s[8:9], s[2:3], exec
	s_cselect_b32 s21, s65, s69
	s_cselect_b32 s94, s64, s68
	s_cselect_b32 s8, 0, 0x700
	s_add_u32 s94, s94, s8
	s_addc_u32 s21, s21, 0
	s_add_u32 s70, s72, 0x100
	s_addc_u32 s71, s73, 0
	s_add_u32 s8, s68, 0x100
	s_addc_u32 s9, s69, 0
	s_add_u32 s74, s72, 0x180
	s_addc_u32 s75, s73, 0
	s_add_u32 s12, s72, 0x40080
	s_addc_u32 s13, s73, 0
	s_add_i32 s95, s67, 0xc000
	v_mov_b32_e32 v232, v134
	s_mov_b32 m0, s95
	s_add_i32 s96, s67, 0xe000
	ds_read_b128 v[34:37], v143
	ds_read_b128 v[38:41], v143 offset:1024
	ds_read_b128 v[42:45], v143 offset:2048
	ds_read_b128 v[46:49], v143 offset:3072
	ds_read_b128 v[50:53], v143 offset:4096
	ds_read_b128 v[54:57], v143 offset:5120
	ds_read_b128 v[58:61], v143 offset:6144
	ds_read_b128 v[62:65], v143 offset:7168
	v_mov_b32_e32 v233, v136
	global_load_lds_dwordx4 v232, s[12:13]
	s_mov_b32 m0, s96
	s_add_u32 s76, s68, 0x180
	global_load_lds_dwordx4 v233, s[12:13]
	s_waitcnt vmcnt(8)
	s_waitcnt lgkmcnt(0)
	s_addc_u32 s77, s69, 0
	s_barrier
	s_waitcnt lgkmcnt(0)
	v_mfma_f32_16x16x32_bf16 v[66:69], v[2:5], v[34:37], 0
	v_mfma_f32_16x16x32_bf16 v[70:73], v[10:13], v[34:37], 0
	v_mfma_f32_16x16x32_bf16 v[74:77], v[2:5], v[42:45], 0
	v_mfma_f32_16x16x32_bf16 v[78:81], v[10:13], v[42:45], 0
	v_mfma_f32_16x16x32_bf16 v[82:85], v[2:5], v[50:53], 0
	v_mfma_f32_16x16x32_bf16 v[86:89], v[10:13], v[50:53], 0
	v_mfma_f32_16x16x32_bf16 v[90:93], v[2:5], v[58:61], 0
	v_mfma_f32_16x16x32_bf16 v[94:97], v[10:13], v[58:61], 0
	v_mfma_f32_16x16x32_bf16 v[66:69], v[6:9], v[38:41], v[66:69]
	v_mfma_f32_16x16x32_bf16 v[70:73], v[14:17], v[38:41], v[70:73]
	v_mfma_f32_16x16x32_bf16 v[74:77], v[6:9], v[46:49], v[74:77]
	v_mfma_f32_16x16x32_bf16 v[78:81], v[14:17], v[46:49], v[78:81]
	v_mfma_f32_16x16x32_bf16 v[82:85], v[6:9], v[54:57], v[82:85]
	v_mfma_f32_16x16x32_bf16 v[86:89], v[14:17], v[54:57], v[86:89]
	v_mfma_f32_16x16x32_bf16 v[90:93], v[6:9], v[62:65], v[90:93]
	v_mfma_f32_16x16x32_bf16 v[94:97], v[14:17], v[62:65], v[94:97]
	v_mfma_f32_16x16x32_bf16 v[98:101], v[18:21], v[34:37], 0
	v_mfma_f32_16x16x32_bf16 v[34:37], v[26:29], v[34:37], 0
	v_mfma_f32_16x16x32_bf16 v[102:105], v[18:21], v[42:45], 0
	v_mfma_f32_16x16x32_bf16 v[42:45], v[26:29], v[42:45], 0
	v_mfma_f32_16x16x32_bf16 v[106:109], v[18:21], v[50:53], 0
	v_mfma_f32_16x16x32_bf16 v[50:53], v[26:29], v[50:53], 0
	v_mfma_f32_16x16x32_bf16 v[110:113], v[18:21], v[58:61], 0
	v_mfma_f32_16x16x32_bf16 v[58:61], v[26:29], v[58:61], 0
	v_mfma_f32_16x16x32_bf16 v[118:121], v[22:25], v[38:41], v[98:101]
	v_mfma_f32_16x16x32_bf16 v[34:37], v[30:33], v[38:41], v[34:37]
	v_mfma_f32_16x16x32_bf16 v[38:41], v[22:25], v[46:49], v[102:105]
	v_mfma_f32_16x16x32_bf16 v[42:45], v[30:33], v[46:49], v[42:45]
	v_mfma_f32_16x16x32_bf16 v[46:49], v[22:25], v[54:57], v[106:109]
	v_mfma_f32_16x16x32_bf16 v[50:53], v[30:33], v[54:57], v[50:53]
	v_mfma_f32_16x16x32_bf16 v[54:57], v[22:25], v[62:65], v[110:113]
	v_mfma_f32_16x16x32_bf16 v[62:65], v[30:33], v[62:65], v[58:61]
	s_barrier
	s_add_i32 s97, s90, s63
	v_mov_b32_e32 v234, v135
	s_mov_b32 m0, s97
	s_add_i32 vcc_lo, s97, 0x2000
	ds_read_b128 v[58:61], v143 offset:16384
	ds_read_b128 v[98:101], v143 offset:17408
	ds_read_b128 v[102:105], v143 offset:18432
	ds_read_b128 v[106:109], v143 offset:19456
	ds_read_b128 v[110:113], v143 offset:20480
	ds_read_b128 v[114:117], v143 offset:21504
	ds_read_b128 v[122:125], v143 offset:22528
	ds_read_b128 v[126:129], v143 offset:23552
	v_mov_b32_e32 v235, v137
	global_load_lds_dwordx4 v234, s[8:9]
	s_mov_b32 m0, vcc_lo
	s_nop 0
	global_load_lds_dwordx4 v235, s[8:9]
	s_add_u32 s8, s68, 0x40100
	s_addc_u32 s9, s69, 0
	s_add_i32 vcc_hi, s91, s63
	s_mov_b32 m0, vcc_hi
	s_add_i32 s34, vcc_hi, 0x2000
	s_nop 0
	global_load_lds_dwordx4 v234, s[8:9]
	s_mov_b32 m0, s34
	s_nop 0
	global_load_lds_dwordx4 v235, s[8:9]
	s_mov_b64 s[8:9], s[70:71]
	s_mov_b32 m0, s67
	s_nop 0
	global_load_lds_dwordx4 v232, s[8:9]
	s_mov_b32 m0, s83
	s_nop 0
	global_load_lds_dwordx4 v233, s[8:9]
	s_waitcnt vmcnt(8)
	s_waitcnt lgkmcnt(0)
	s_barrier
	s_waitcnt lgkmcnt(0)
	v_mfma_f32_16x16x32_bf16 v[144:147], v[2:5], v[58:61], 0
	v_mfma_f32_16x16x32_bf16 v[148:151], v[10:13], v[58:61], 0
	v_mfma_f32_16x16x32_bf16 v[152:155], v[2:5], v[102:105], 0
	v_mfma_f32_16x16x32_bf16 v[156:159], v[10:13], v[102:105], 0
	v_mfma_f32_16x16x32_bf16 v[160:163], v[2:5], v[110:113], 0
	v_mfma_f32_16x16x32_bf16 v[164:167], v[10:13], v[110:113], 0
	v_mfma_f32_16x16x32_bf16 v[2:5], v[2:5], v[122:125], 0
	v_mfma_f32_16x16x32_bf16 v[10:13], v[10:13], v[122:125], 0
	v_mfma_f32_16x16x32_bf16 v[168:171], v[6:9], v[98:101], v[144:147]
	v_mfma_f32_16x16x32_bf16 v[146:149], v[14:17], v[98:101], v[148:151]
	v_mfma_f32_16x16x32_bf16 v[150:153], v[6:9], v[106:109], v[152:155]
	v_mfma_f32_16x16x32_bf16 v[154:157], v[14:17], v[106:109], v[156:159]
	v_mfma_f32_16x16x32_bf16 v[158:161], v[6:9], v[114:117], v[160:163]
	v_mfma_f32_16x16x32_bf16 v[2:5], v[6:9], v[126:129], v[2:5]
	v_mfma_f32_16x16x32_bf16 v[6:9], v[14:17], v[126:129], v[10:13]
	v_mfma_f32_16x16x32_bf16 v[162:165], v[14:17], v[114:117], v[164:167]
	v_mfma_f32_16x16x32_bf16 v[10:13], v[18:21], v[58:61], 0
	v_mfma_f32_16x16x32_bf16 v[14:17], v[26:29], v[58:61], 0
	v_mfma_f32_16x16x32_bf16 v[58:61], v[18:21], v[102:105], 0
	v_mfma_f32_16x16x32_bf16 v[102:105], v[26:29], v[102:105], 0
	v_mfma_f32_16x16x32_bf16 v[172:175], v[18:21], v[110:113], 0
	v_mfma_f32_16x16x32_bf16 v[110:113], v[26:29], v[110:113], 0
	v_mfma_f32_16x16x32_bf16 v[18:21], v[18:21], v[122:125], 0
	v_mfma_f32_16x16x32_bf16 v[26:29], v[26:29], v[122:125], 0
	v_mfma_f32_16x16x32_bf16 v[176:179], v[22:25], v[98:101], v[10:13]
	v_mfma_f32_16x16x32_bf16 v[14:17], v[30:33], v[98:101], v[14:17]
	v_mfma_f32_16x16x32_bf16 v[180:183], v[22:25], v[106:109], v[58:61]
	v_mfma_f32_16x16x32_bf16 v[184:187], v[30:33], v[106:109], v[102:105]
	v_mfma_f32_16x16x32_bf16 v[172:175], v[22:25], v[114:117], v[172:175]
	v_mfma_f32_16x16x32_bf16 v[188:191], v[30:33], v[114:117], v[110:113]
	v_mfma_f32_16x16x32_bf16 v[22:25], v[22:25], v[126:129], v[18:21]
	v_mfma_f32_16x16x32_bf16 v[30:33], v[30:33], v[126:129], v[26:29]
	s_barrier
	s_add_i32 s35, 0, 0x18000
	s_add_i32 s80, 0, 0x1c000
	v_add_u32_e32 v144, s35, v139
	v_add_u32_e32 v145, s80, v139
	ds_read_b128 v[10:13], v144
	ds_read_b128 v[192:195], v144 offset:1024
	ds_read_b128 v[18:21], v144 offset:2048
	ds_read_b128 v[196:199], v144 offset:3072
	ds_read_b128 v[200:203], v145
	ds_read_b128 v[204:207], v145 offset:1024
	ds_read_b128 v[208:211], v145 offset:2048
	ds_read_b128 v[212:215], v145 offset:3072
	s_add_u32 s8, s72, 0x40100
	s_addc_u32 s9, s73, 0
	s_mov_b32 m0, s84
	ds_read_b128 v[26:29], v143 offset:32768
	ds_read_b128 v[102:105], v143 offset:33792
	ds_read_b128 v[110:113], v143 offset:34816
	ds_read_b128 v[216:219], v143 offset:35840
	ds_read_b128 v[126:129], v143 offset:36864
	ds_read_b128 v[220:223], v143 offset:37888
	ds_read_b128 v[224:227], v143 offset:38912
	ds_read_b128 v[228:231], v143 offset:39936
	s_nop 0
	global_load_lds_dwordx4 v232, s[8:9]
	s_mov_b32 m0, s85
	s_nop 0
	global_load_lds_dwordx4 v233, s[8:9]
	s_waitcnt vmcnt(8)
	s_waitcnt lgkmcnt(0)
	s_barrier
	s_waitcnt lgkmcnt(0)
	v_mfma_f32_16x16x32_bf16 v[58:61], v[10:13], v[26:29], v[66:69]
	v_mfma_f32_16x16x32_bf16 v[66:69], v[18:21], v[26:29], v[70:73]
	v_mfma_f32_16x16x32_bf16 v[70:73], v[10:13], v[110:113], v[74:77]
	v_mfma_f32_16x16x32_bf16 v[74:77], v[18:21], v[110:113], v[78:81]
	v_mfma_f32_16x16x32_bf16 v[78:81], v[10:13], v[126:129], v[82:85]
	v_mfma_f32_16x16x32_bf16 v[82:85], v[18:21], v[126:129], v[86:89]
	v_mfma_f32_16x16x32_bf16 v[86:89], v[10:13], v[224:227], v[90:93]
	v_mfma_f32_16x16x32_bf16 v[94:97], v[18:21], v[224:227], v[94:97]
	v_mfma_f32_16x16x32_bf16 v[122:125], v[192:195], v[102:105], v[58:61]
	v_mfma_f32_16x16x32_bf16 v[114:117], v[196:199], v[102:105], v[66:69]
	v_mfma_f32_16x16x32_bf16 v[106:109], v[192:195], v[216:219], v[70:73]
	v_mfma_f32_16x16x32_bf16 v[98:101], v[196:199], v[216:219], v[74:77]
	v_mfma_f32_16x16x32_bf16 v[90:93], v[192:195], v[220:223], v[78:81]
	v_mfma_f32_16x16x32_bf16 v[82:85], v[196:199], v[220:223], v[82:85]
	v_mfma_f32_16x16x32_bf16 v[74:77], v[192:195], v[228:231], v[86:89]
	v_mfma_f32_16x16x32_bf16 v[58:61], v[196:199], v[228:231], v[94:97]
	v_mfma_f32_16x16x32_bf16 v[66:69], v[200:203], v[26:29], v[118:121]
	v_mfma_f32_16x16x32_bf16 v[26:29], v[208:211], v[26:29], v[34:37]
	v_mfma_f32_16x16x32_bf16 v[34:37], v[200:203], v[110:113], v[38:41]
	v_mfma_f32_16x16x32_bf16 v[38:41], v[208:211], v[110:113], v[42:45]
	v_mfma_f32_16x16x32_bf16 v[42:45], v[200:203], v[126:129], v[46:49]
	v_mfma_f32_16x16x32_bf16 v[46:49], v[208:211], v[126:129], v[50:53]
	v_mfma_f32_16x16x32_bf16 v[50:53], v[200:203], v[224:227], v[54:57]
	v_mfma_f32_16x16x32_bf16 v[54:57], v[208:211], v[224:227], v[62:65]
	v_mfma_f32_16x16x32_bf16 v[126:129], v[204:207], v[102:105], v[66:69]
	v_mfma_f32_16x16x32_bf16 v[118:121], v[212:215], v[102:105], v[26:29]
	v_mfma_f32_16x16x32_bf16 v[110:113], v[204:207], v[216:219], v[34:37]
	v_mfma_f32_16x16x32_bf16 v[102:105], v[212:215], v[216:219], v[38:41]
	v_mfma_f32_16x16x32_bf16 v[94:97], v[204:207], v[220:223], v[42:45]
	v_mfma_f32_16x16x32_bf16 v[86:89], v[212:215], v[220:223], v[46:49]
	v_mfma_f32_16x16x32_bf16 v[78:81], v[204:207], v[228:231], v[50:53]
	v_mfma_f32_16x16x32_bf16 v[66:69], v[212:215], v[228:231], v[54:57]
	s_barrier
	s_add_i32 s35, s35, s63
	s_add_i32 s11, s35, 0x2000
	s_mov_b32 m0, s35
	s_add_u32 s12, s68, 0x40180
	ds_read_b128 v[38:41], v143 offset:49152
	ds_read_b128 v[46:49], v143 offset:50176
	ds_read_b128 v[54:57], v143 offset:51200
	ds_read_b128 v[216:219], v143 offset:52224
	ds_read_b128 v[70:73], v143 offset:53248
	ds_read_b128 v[220:223], v143 offset:54272
	ds_read_b128 v[224:227], v143 offset:55296
	ds_read_b128 v[228:231], v143 offset:56320
	s_addc_u32 s13, s69, 0
	global_load_lds_dwordx4 v234, s[76:77]
	s_mov_b32 m0, s11
	s_add_i32 s80, s80, s63
	global_load_lds_dwordx4 v235, s[76:77]
	s_mov_b32 m0, s80
	s_add_i32 s8, s80, 0x2000
	s_nop 0
	global_load_lds_dwordx4 v234, s[12:13]
	s_mov_b32 m0, s8
	s_nop 0
	global_load_lds_dwordx4 v235, s[12:13]
	s_mov_b32 m0, s87
	s_nop 0
	global_load_lds_dwordx4 v232, s[74:75]
	s_mov_b32 m0, s88
	s_nop 0
	global_load_lds_dwordx4 v233, s[74:75]
	s_waitcnt vmcnt(8)
	s_waitcnt lgkmcnt(0)
	s_barrier
	s_waitcnt lgkmcnt(0)
	v_mfma_f32_16x16x32_bf16 v[26:29], v[10:13], v[38:41], v[168:171]
	v_mfma_f32_16x16x32_bf16 v[34:37], v[18:21], v[38:41], v[146:149]
	v_mfma_f32_16x16x32_bf16 v[42:45], v[10:13], v[54:57], v[150:153]
	v_mfma_f32_16x16x32_bf16 v[146:149], v[18:21], v[54:57], v[154:157]
	v_mfma_f32_16x16x32_bf16 v[150:153], v[10:13], v[70:73], v[158:161]
	v_mfma_f32_16x16x32_bf16 v[154:157], v[18:21], v[70:73], v[162:165]
	v_mfma_f32_16x16x32_bf16 v[2:5], v[10:13], v[224:227], v[2:5]
	v_mfma_f32_16x16x32_bf16 v[6:9], v[18:21], v[224:227], v[6:9]
	v_mfma_f32_16x16x32_bf16 v[62:65], v[192:195], v[46:49], v[26:29]
	v_mfma_f32_16x16x32_bf16 v[50:53], v[196:199], v[46:49], v[34:37]
	v_mfma_f32_16x16x32_bf16 v[42:45], v[192:195], v[216:219], v[42:45]
	v_mfma_f32_16x16x32_bf16 v[34:37], v[196:199], v[216:219], v[146:149]
	v_mfma_f32_16x16x32_bf16 v[26:29], v[192:195], v[220:223], v[150:153]
	v_mfma_f32_16x16x32_bf16 v[18:21], v[196:199], v[220:223], v[154:157]
	v_mfma_f32_16x16x32_bf16 v[10:13], v[192:195], v[228:231], v[2:5]
	v_mfma_f32_16x16x32_bf16 v[2:5], v[196:199], v[228:231], v[6:9]
	v_mfma_f32_16x16x32_bf16 v[6:9], v[200:203], v[38:41], v[176:179]
	v_mfma_f32_16x16x32_bf16 v[14:17], v[208:211], v[38:41], v[14:17]
	v_mfma_f32_16x16x32_bf16 v[38:41], v[200:203], v[54:57], v[180:183]
	v_mfma_f32_16x16x32_bf16 v[146:149], v[208:211], v[54:57], v[184:187]
	v_mfma_f32_16x16x32_bf16 v[150:153], v[200:203], v[70:73], v[172:175]
	v_mfma_f32_16x16x32_bf16 v[154:157], v[208:211], v[70:73], v[188:191]
	v_mfma_f32_16x16x32_bf16 v[158:161], v[200:203], v[224:227], v[22:25]
	v_mfma_f32_16x16x32_bf16 v[162:165], v[208:211], v[224:227], v[30:33]
	v_mfma_f32_16x16x32_bf16 v[70:73], v[204:207], v[46:49], v[6:9]
	v_mfma_f32_16x16x32_bf16 v[54:57], v[212:215], v[46:49], v[14:17]
	v_mfma_f32_16x16x32_bf16 v[46:49], v[204:207], v[216:219], v[38:41]
	v_mfma_f32_16x16x32_bf16 v[38:41], v[212:215], v[216:219], v[146:149]
	v_mfma_f32_16x16x32_bf16 v[30:33], v[204:207], v[220:223], v[150:153]
	v_mfma_f32_16x16x32_bf16 v[22:25], v[212:215], v[220:223], v[154:157]
	v_mfma_f32_16x16x32_bf16 v[14:17], v[204:207], v[228:231], v[158:161]
	v_mfma_f32_16x16x32_bf16 v[6:9], v[212:215], v[228:231], v[162:165]
	s_barrier
	s_add_u32 s9, s68, 0x200
	s_addc_u32 s78, s69, 0
	s_mov_b32 s62, 0

.LBB0_327:
	s_ashr_i32 s27, s26, 31
	s_lshl_b64 s[8:9], s[26:27], 19
	s_add_u32 s64, s16, s8
	s_addc_u32 s65, s79, s9
	s_and_b64 s[8:9], s[2:3], exec
	ds_read_b128 v[2:5], v143
	ds_read_b128 v[6:9], v143 offset:1024
	ds_read_b128 v[10:13], v143 offset:2048
	ds_read_b128 v[14:17], v143 offset:3072
	ds_read_b128 v[18:21], v144
	ds_read_b128 v[22:25], v144 offset:1024
	ds_read_b128 v[26:29], v144 offset:2048
	ds_read_b128 v[30:33], v144 offset:3072
	s_cselect_b32 s15, s65, s71
	s_cselect_b32 s27, s64, s70
	s_cselect_b32 s8, 0, 0x700
	s_add_u32 s27, s27, s8
	s_addc_u32 s15, s15, 0
	s_ashr_i32 s21, s20, 31
	s_lshl_b64 s[8:9], s[20:21], 19
	s_add_u32 s66, s17, s8
	s_addc_u32 s67, s63, s9
	s_and_b64 s[8:9], s[2:3], exec
	s_cselect_b32 s21, s67, s69
	s_cselect_b32 s95, s66, s68
	s_cselect_b32 s8, 0, 0x700
	s_add_u32 s95, s95, s8
	s_addc_u32 s21, s21, 0
	s_add_u32 s72, s70, 0x100
	s_addc_u32 s73, s71, 0
	s_add_u32 s8, s68, 0x100
	s_addc_u32 s9, s69, 0
	s_add_u32 s74, s70, 0x180
	s_addc_u32 s75, s71, 0
	s_add_u32 s22, s70, 0x40080
	s_addc_u32 s23, s71, 0
	s_add_i32 s96, s84, 0xc000
	v_mov_b32_e32 v238, v134
	s_mov_b32 m0, s96
	s_add_i32 s97, s84, 0xe000
	ds_read_b128 v[34:37], v145
	ds_read_b128 v[38:41], v145 offset:1024
	ds_read_b128 v[42:45], v145 offset:2048
	ds_read_b128 v[46:49], v145 offset:3072
	ds_read_b128 v[50:53], v145 offset:4096
	ds_read_b128 v[54:57], v145 offset:5120
	ds_read_b128 v[58:61], v145 offset:6144
	ds_read_b128 v[62:65], v145 offset:7168
	v_mov_b32_e32 v239, v136
	global_load_lds_dwordx4 v238, s[22:23]
	s_mov_b32 m0, s97
	s_add_u32 s76, s68, 0x180
	global_load_lds_dwordx4 v239, s[22:23]
	s_waitcnt vmcnt(8)
	s_waitcnt lgkmcnt(0)
	s_addc_u32 s77, s69, 0
	s_barrier
	s_waitcnt lgkmcnt(0)
	v_mfma_f32_16x16x32_bf16 v[66:69], v[2:5], v[34:37], 0
	v_mfma_f32_16x16x32_bf16 v[70:73], v[10:13], v[34:37], 0
	v_mfma_f32_16x16x32_bf16 v[74:77], v[2:5], v[42:45], 0
	v_mfma_f32_16x16x32_bf16 v[78:81], v[10:13], v[42:45], 0
	v_mfma_f32_16x16x32_bf16 v[82:85], v[2:5], v[50:53], 0
	v_mfma_f32_16x16x32_bf16 v[86:89], v[10:13], v[50:53], 0
	v_mfma_f32_16x16x32_bf16 v[90:93], v[2:5], v[58:61], 0
	v_mfma_f32_16x16x32_bf16 v[94:97], v[10:13], v[58:61], 0
	v_mfma_f32_16x16x32_bf16 v[66:69], v[6:9], v[38:41], v[66:69]
	v_mfma_f32_16x16x32_bf16 v[70:73], v[14:17], v[38:41], v[70:73]
	v_mfma_f32_16x16x32_bf16 v[74:77], v[6:9], v[46:49], v[74:77]
	v_mfma_f32_16x16x32_bf16 v[78:81], v[14:17], v[46:49], v[78:81]
	v_mfma_f32_16x16x32_bf16 v[82:85], v[6:9], v[54:57], v[82:85]
	v_mfma_f32_16x16x32_bf16 v[86:89], v[14:17], v[54:57], v[86:89]
	v_mfma_f32_16x16x32_bf16 v[90:93], v[6:9], v[62:65], v[90:93]
	v_mfma_f32_16x16x32_bf16 v[94:97], v[14:17], v[62:65], v[94:97]
	v_mfma_f32_16x16x32_bf16 v[98:101], v[18:21], v[34:37], 0
	v_mfma_f32_16x16x32_bf16 v[34:37], v[26:29], v[34:37], 0
	v_mfma_f32_16x16x32_bf16 v[102:105], v[18:21], v[42:45], 0
	v_mfma_f32_16x16x32_bf16 v[42:45], v[26:29], v[42:45], 0
	v_mfma_f32_16x16x32_bf16 v[106:109], v[18:21], v[50:53], 0
	v_mfma_f32_16x16x32_bf16 v[50:53], v[26:29], v[50:53], 0
	v_mfma_f32_16x16x32_bf16 v[110:113], v[18:21], v[58:61], 0
	v_mfma_f32_16x16x32_bf16 v[58:61], v[26:29], v[58:61], 0
	v_mfma_f32_16x16x32_bf16 v[114:117], v[22:25], v[38:41], v[98:101]
	v_mfma_f32_16x16x32_bf16 v[34:37], v[30:33], v[38:41], v[34:37]
	v_mfma_f32_16x16x32_bf16 v[102:105], v[22:25], v[46:49], v[102:105]
	v_mfma_f32_16x16x32_bf16 v[42:45], v[30:33], v[46:49], v[42:45]
	v_mfma_f32_16x16x32_bf16 v[46:49], v[22:25], v[54:57], v[106:109]
	v_mfma_f32_16x16x32_bf16 v[50:53], v[30:33], v[54:57], v[50:53]
	v_mfma_f32_16x16x32_bf16 v[110:113], v[22:25], v[62:65], v[110:113]
	v_mfma_f32_16x16x32_bf16 v[58:61], v[30:33], v[62:65], v[58:61]
	s_barrier
	s_add_i32 vcc_lo, s92, s81
	v_mov_b32_e32 v240, v135
	s_mov_b32 m0, vcc_lo
	s_add_i32 vcc_hi, vcc_lo, 0x2000
	ds_read_b128 v[38:41], v145 offset:16384
	ds_read_b128 v[54:57], v145 offset:17408
	ds_read_b128 v[62:65], v145 offset:18432
	ds_read_b128 v[98:101], v145 offset:19456
	ds_read_b128 v[106:109], v145 offset:20480
	ds_read_b128 v[118:121], v145 offset:21504
	ds_read_b128 v[122:125], v145 offset:22528
	ds_read_b128 v[126:129], v145 offset:23552
	v_mov_b32_e32 v241, v137
	global_load_lds_dwordx4 v240, s[8:9]
	s_mov_b32 m0, vcc_hi
	s_nop 0
	global_load_lds_dwordx4 v241, s[8:9]
	s_add_u32 s8, s68, 0x40100
	s_addc_u32 s9, s69, 0
	s_add_i32 s34, s93, s81
	s_mov_b32 m0, s34
	s_add_i32 s35, s34, 0x2000
	s_nop 0
	global_load_lds_dwordx4 v240, s[8:9]
	s_mov_b32 m0, s35
	s_nop 0
	global_load_lds_dwordx4 v241, s[8:9]
	s_mov_b64 s[8:9], s[72:73]
	s_mov_b32 m0, s84
	s_nop 0
	global_load_lds_dwordx4 v238, s[8:9]
	s_mov_b32 m0, s85
	s_nop 0
	global_load_lds_dwordx4 v239, s[8:9]
	s_waitcnt vmcnt(8)
	s_waitcnt lgkmcnt(0)
	s_barrier
	s_waitcnt lgkmcnt(0)
	v_mfma_f32_16x16x32_bf16 v[146:149], v[2:5], v[38:41], 0
	v_mfma_f32_16x16x32_bf16 v[150:153], v[10:13], v[38:41], 0
	v_mfma_f32_16x16x32_bf16 v[154:157], v[2:5], v[62:65], 0
	v_mfma_f32_16x16x32_bf16 v[158:161], v[10:13], v[62:65], 0
	v_mfma_f32_16x16x32_bf16 v[162:165], v[2:5], v[106:109], 0
	v_mfma_f32_16x16x32_bf16 v[166:169], v[10:13], v[106:109], 0
	v_mfma_f32_16x16x32_bf16 v[2:5], v[2:5], v[122:125], 0
	v_mfma_f32_16x16x32_bf16 v[10:13], v[10:13], v[122:125], 0
	v_mfma_f32_16x16x32_bf16 v[170:173], v[6:9], v[54:57], v[146:149]
	v_mfma_f32_16x16x32_bf16 v[148:151], v[14:17], v[54:57], v[150:153]
	v_mfma_f32_16x16x32_bf16 v[152:155], v[6:9], v[98:101], v[154:157]
	v_mfma_f32_16x16x32_bf16 v[156:159], v[14:17], v[98:101], v[158:161]
	v_mfma_f32_16x16x32_bf16 v[160:163], v[6:9], v[118:121], v[162:165]
	v_mfma_f32_16x16x32_bf16 v[2:5], v[6:9], v[126:129], v[2:5]
	v_mfma_f32_16x16x32_bf16 v[6:9], v[14:17], v[126:129], v[10:13]
	v_mfma_f32_16x16x32_bf16 v[164:167], v[14:17], v[118:121], v[166:169]
	v_mfma_f32_16x16x32_bf16 v[10:13], v[18:21], v[38:41], 0
	v_mfma_f32_16x16x32_bf16 v[14:17], v[26:29], v[38:41], 0
	v_mfma_f32_16x16x32_bf16 v[38:41], v[18:21], v[62:65], 0
	v_mfma_f32_16x16x32_bf16 v[62:65], v[26:29], v[62:65], 0
	v_mfma_f32_16x16x32_bf16 v[174:177], v[18:21], v[106:109], 0
	v_mfma_f32_16x16x32_bf16 v[106:109], v[26:29], v[106:109], 0
	v_mfma_f32_16x16x32_bf16 v[18:21], v[18:21], v[122:125], 0
	v_mfma_f32_16x16x32_bf16 v[26:29], v[26:29], v[122:125], 0
	v_mfma_f32_16x16x32_bf16 v[178:181], v[22:25], v[54:57], v[10:13]
	v_mfma_f32_16x16x32_bf16 v[14:17], v[30:33], v[54:57], v[14:17]
	v_mfma_f32_16x16x32_bf16 v[182:185], v[22:25], v[98:101], v[38:41]
	v_mfma_f32_16x16x32_bf16 v[186:189], v[30:33], v[98:101], v[62:65]
	v_mfma_f32_16x16x32_bf16 v[174:177], v[22:25], v[118:121], v[174:177]
	v_mfma_f32_16x16x32_bf16 v[190:193], v[30:33], v[118:121], v[106:109]
	v_mfma_f32_16x16x32_bf16 v[22:25], v[22:25], v[126:129], v[18:21]
	v_mfma_f32_16x16x32_bf16 v[30:33], v[30:33], v[126:129], v[26:29]
	s_barrier
	s_add_i32 s11, 0, 0x18000
	s_add_i32 s24, 0, 0x1c000
	v_add_u32_e32 v146, s11, v139
	v_add_u32_e32 v147, s24, v139
	ds_read_b128 v[10:13], v146
	ds_read_b128 v[194:197], v146 offset:1024
	ds_read_b128 v[18:21], v146 offset:2048
	ds_read_b128 v[198:201], v146 offset:3072
	ds_read_b128 v[202:205], v147
	ds_read_b128 v[206:209], v147 offset:1024
	ds_read_b128 v[210:213], v147 offset:2048
	ds_read_b128 v[214:217], v147 offset:3072
	s_add_u32 s8, s70, 0x40100
	s_addc_u32 s9, s71, 0
	s_mov_b32 m0, s86
	ds_read_b128 v[26:29], v145 offset:32768
	ds_read_b128 v[62:65], v145 offset:33792
	ds_read_b128 v[122:125], v145 offset:34816
	ds_read_b128 v[218:221], v145 offset:35840
	ds_read_b128 v[222:225], v145 offset:36864
	ds_read_b128 v[226:229], v145 offset:37888
	ds_read_b128 v[230:233], v145 offset:38912
	ds_read_b128 v[234:237], v145 offset:39936
	s_nop 0
	global_load_lds_dwordx4 v238, s[8:9]
	s_mov_b32 m0, s87
	s_nop 0
	global_load_lds_dwordx4 v239, s[8:9]
	s_waitcnt vmcnt(8)
	s_waitcnt lgkmcnt(0)
	s_barrier
	s_waitcnt lgkmcnt(0)
	v_mfma_f32_16x16x32_bf16 v[38:41], v[10:13], v[26:29], v[66:69]
	v_mfma_f32_16x16x32_bf16 v[54:57], v[18:21], v[26:29], v[70:73]
	v_mfma_f32_16x16x32_bf16 v[66:69], v[10:13], v[122:125], v[74:77]
	v_mfma_f32_16x16x32_bf16 v[70:73], v[18:21], v[122:125], v[78:81]
	v_mfma_f32_16x16x32_bf16 v[74:77], v[10:13], v[222:225], v[82:85]
	v_mfma_f32_16x16x32_bf16 v[78:81], v[18:21], v[222:225], v[86:89]
	v_mfma_f32_16x16x32_bf16 v[82:85], v[10:13], v[230:233], v[90:93]
	v_mfma_f32_16x16x32_bf16 v[90:93], v[18:21], v[230:233], v[94:97]
	v_mfma_f32_16x16x32_bf16 v[126:129], v[194:197], v[62:65], v[38:41]
	v_mfma_f32_16x16x32_bf16 v[118:121], v[198:201], v[62:65], v[54:57]
	v_mfma_f32_16x16x32_bf16 v[106:109], v[194:197], v[218:221], v[66:69]
	v_mfma_f32_16x16x32_bf16 v[98:101], v[198:201], v[218:221], v[70:73]
	v_mfma_f32_16x16x32_bf16 v[86:89], v[194:197], v[226:229], v[74:77]
	v_mfma_f32_16x16x32_bf16 v[70:73], v[198:201], v[226:229], v[78:81]
	v_mfma_f32_16x16x32_bf16 v[54:57], v[194:197], v[234:237], v[82:85]
	v_mfma_f32_16x16x32_bf16 v[38:41], v[198:201], v[234:237], v[90:93]
	v_mfma_f32_16x16x32_bf16 v[66:69], v[202:205], v[26:29], v[114:117]
	v_mfma_f32_16x16x32_bf16 v[26:29], v[210:213], v[26:29], v[34:37]
	v_mfma_f32_16x16x32_bf16 v[34:37], v[202:205], v[122:125], v[102:105]
	v_mfma_f32_16x16x32_bf16 v[42:45], v[210:213], v[122:125], v[42:45]
	v_mfma_f32_16x16x32_bf16 v[46:49], v[202:205], v[222:225], v[46:49]
	v_mfma_f32_16x16x32_bf16 v[50:53], v[210:213], v[222:225], v[50:53]
	v_mfma_f32_16x16x32_bf16 v[74:77], v[202:205], v[230:233], v[110:113]
	v_mfma_f32_16x16x32_bf16 v[58:61], v[210:213], v[230:233], v[58:61]
	v_mfma_f32_16x16x32_bf16 v[122:125], v[206:209], v[62:65], v[66:69]
	v_mfma_f32_16x16x32_bf16 v[114:117], v[214:217], v[62:65], v[26:29]
	v_mfma_f32_16x16x32_bf16 v[110:113], v[206:209], v[218:221], v[34:37]
	v_mfma_f32_16x16x32_bf16 v[102:105], v[214:217], v[218:221], v[42:45]
	v_mfma_f32_16x16x32_bf16 v[94:97], v[206:209], v[226:229], v[46:49]
	v_mfma_f32_16x16x32_bf16 v[78:81], v[214:217], v[226:229], v[50:53]
	v_mfma_f32_16x16x32_bf16 v[62:65], v[206:209], v[234:237], v[74:77]
	v_mfma_f32_16x16x32_bf16 v[46:49], v[214:217], v[234:237], v[58:61]
	s_barrier
	s_add_i32 s11, s11, s81
	s_add_i32 s80, s11, 0x2000
	s_mov_b32 m0, s11
	s_add_u32 s22, s68, 0x40180
	ds_read_b128 v[42:45], v145 offset:49152
	ds_read_b128 v[58:61], v145 offset:50176
	ds_read_b128 v[74:77], v145 offset:51200
	ds_read_b128 v[218:221], v145 offset:52224
	ds_read_b128 v[90:93], v145 offset:53248
	ds_read_b128 v[222:225], v145 offset:54272
	ds_read_b128 v[226:229], v145 offset:55296
	ds_read_b128 v[230:233], v145 offset:56320
	s_addc_u32 s23, s69, 0
	global_load_lds_dwordx4 v240, s[76:77]
	s_mov_b32 m0, s80
	s_add_i32 s8, s24, s81
	global_load_lds_dwordx4 v241, s[76:77]
	s_mov_b32 m0, s8
	s_add_i32 s9, s8, 0x2000
	s_nop 0
	global_load_lds_dwordx4 v240, s[22:23]
	s_mov_b32 m0, s9
	s_nop 0
	global_load_lds_dwordx4 v241, s[22:23]
	s_mov_b32 m0, s89
	s_nop 0
	global_load_lds_dwordx4 v238, s[74:75]
	s_mov_b32 m0, s90
	s_nop 0
	global_load_lds_dwordx4 v239, s[74:75]
	s_waitcnt vmcnt(8)
	s_waitcnt lgkmcnt(0)
	s_barrier
	s_waitcnt lgkmcnt(0)
	v_mfma_f32_16x16x32_bf16 v[26:29], v[10:13], v[42:45], v[170:173]
	v_mfma_f32_16x16x32_bf16 v[34:37], v[18:21], v[42:45], v[148:151]
	v_mfma_f32_16x16x32_bf16 v[50:53], v[10:13], v[74:77], v[152:155]
	v_mfma_f32_16x16x32_bf16 v[148:151], v[18:21], v[74:77], v[156:159]
	v_mfma_f32_16x16x32_bf16 v[152:155], v[10:13], v[90:93], v[160:163]
	v_mfma_f32_16x16x32_bf16 v[156:159], v[18:21], v[90:93], v[164:167]
	v_mfma_f32_16x16x32_bf16 v[2:5], v[10:13], v[226:229], v[2:5]
	v_mfma_f32_16x16x32_bf16 v[6:9], v[18:21], v[226:229], v[6:9]
	v_mfma_f32_16x16x32_bf16 v[82:85], v[194:197], v[58:61], v[26:29]
	v_mfma_f32_16x16x32_bf16 v[66:69], v[198:201], v[58:61], v[34:37]
	v_mfma_f32_16x16x32_bf16 v[50:53], v[194:197], v[218:221], v[50:53]
	v_mfma_f32_16x16x32_bf16 v[34:37], v[198:201], v[218:221], v[148:151]
	v_mfma_f32_16x16x32_bf16 v[26:29], v[194:197], v[222:225], v[152:155]
	v_mfma_f32_16x16x32_bf16 v[18:21], v[198:201], v[222:225], v[156:159]
	v_mfma_f32_16x16x32_bf16 v[10:13], v[194:197], v[230:233], v[2:5]
	v_mfma_f32_16x16x32_bf16 v[2:5], v[198:201], v[230:233], v[6:9]
	v_mfma_f32_16x16x32_bf16 v[6:9], v[202:205], v[42:45], v[178:181]
	v_mfma_f32_16x16x32_bf16 v[14:17], v[210:213], v[42:45], v[14:17]
	v_mfma_f32_16x16x32_bf16 v[42:45], v[202:205], v[74:77], v[182:185]
	v_mfma_f32_16x16x32_bf16 v[148:151], v[210:213], v[74:77], v[186:189]
	v_mfma_f32_16x16x32_bf16 v[152:155], v[202:205], v[90:93], v[174:177]
	v_mfma_f32_16x16x32_bf16 v[156:159], v[210:213], v[90:93], v[190:193]
	v_mfma_f32_16x16x32_bf16 v[160:163], v[202:205], v[226:229], v[22:25]
	v_mfma_f32_16x16x32_bf16 v[164:167], v[210:213], v[226:229], v[30:33]
	v_mfma_f32_16x16x32_bf16 v[90:93], v[206:209], v[58:61], v[6:9]
	v_mfma_f32_16x16x32_bf16 v[74:77], v[214:217], v[58:61], v[14:17]
	v_mfma_f32_16x16x32_bf16 v[58:61], v[206:209], v[218:221], v[42:45]
	v_mfma_f32_16x16x32_bf16 v[42:45], v[214:217], v[218:221], v[148:151]
	v_mfma_f32_16x16x32_bf16 v[30:33], v[206:209], v[222:225], v[152:155]
	v_mfma_f32_16x16x32_bf16 v[22:25], v[214:217], v[222:225], v[156:159]
	v_mfma_f32_16x16x32_bf16 v[14:17], v[206:209], v[230:233], v[160:163]
	v_mfma_f32_16x16x32_bf16 v[6:9], v[214:217], v[230:233], v[164:167]
	s_barrier
	s_add_u32 s78, s68, 0x200
	s_addc_u32 s62, s69, 0
	s_mov_b32 s22, 0

.LBB0_618:
	s_ashr_i32 s21, s20, 31
	s_lshl_b64 s[8:9], s[20:21], 19
	s_add_u32 s26, s16, s8
	s_addc_u32 s27, s79, s9
	s_and_b64 s[8:9], s[2:3], exec
	ds_read_b128 v[2:5], v141
	ds_read_b128 v[6:9], v141 offset:1024
	ds_read_b128 v[10:13], v141 offset:2048
	ds_read_b128 v[14:17], v141 offset:3072
	ds_read_b128 v[18:21], v142
	ds_read_b128 v[22:25], v142 offset:1024
	ds_read_b128 v[26:29], v142 offset:2048
	ds_read_b128 v[30:33], v142 offset:3072
	s_cselect_b32 s21, s27, s43
	s_cselect_b32 s76, s26, s42
	s_cselect_b32 s8, 0, 0x700
	s_add_u32 s76, s76, s8
	s_addc_u32 s21, s21, 0
	s_ashr_i32 s19, s18, 31
	s_lshl_b64 s[8:9], s[18:19], 19
	s_add_u32 s28, s15, s8
	s_addc_u32 s29, s17, s9
	s_and_b64 s[8:9], s[2:3], exec
	s_cselect_b32 s19, s29, s39
	s_cselect_b32 s77, s28, s38
	s_cselect_b32 s8, 0, 0x700
	s_add_u32 s77, s77, s8
	s_addc_u32 s19, s19, 0
	s_add_u32 s40, s42, 0x100
	s_addc_u32 s41, s43, 0
	s_add_u32 s8, s38, 0x100
	s_addc_u32 s9, s39, 0
	s_add_u32 s44, s42, 0x180
	s_addc_u32 s45, s43, 0
	s_add_u32 s22, s42, 0x40080
	s_addc_u32 s23, s43, 0
	s_add_i32 s80, s31, 0xc000
	v_mov_b32_e32 v232, v134
	s_mov_b32 m0, s80
	s_add_i32 s81, s31, 0xe000
	ds_read_b128 v[34:37], v143
	ds_read_b128 v[38:41], v143 offset:1024
	ds_read_b128 v[42:45], v143 offset:2048
	ds_read_b128 v[46:49], v143 offset:3072
	ds_read_b128 v[50:53], v143 offset:4096
	ds_read_b128 v[54:57], v143 offset:5120
	ds_read_b128 v[58:61], v143 offset:6144
	ds_read_b128 v[62:65], v143 offset:7168
	v_mov_b32_e32 v233, v136
	global_load_lds_dwordx4 v232, s[22:23]
	s_mov_b32 m0, s81
	s_add_u32 s48, s38, 0x180
	global_load_lds_dwordx4 v233, s[22:23]
	s_waitcnt vmcnt(8)
	s_waitcnt lgkmcnt(0)
	s_addc_u32 s49, s39, 0
	s_barrier
	s_waitcnt lgkmcnt(0)
	v_mfma_f32_16x16x32_bf16 v[66:69], v[2:5], v[34:37], 0
	v_mfma_f32_16x16x32_bf16 v[70:73], v[10:13], v[34:37], 0
	v_mfma_f32_16x16x32_bf16 v[74:77], v[2:5], v[42:45], 0
	v_mfma_f32_16x16x32_bf16 v[78:81], v[10:13], v[42:45], 0
	v_mfma_f32_16x16x32_bf16 v[82:85], v[2:5], v[50:53], 0
	v_mfma_f32_16x16x32_bf16 v[86:89], v[10:13], v[50:53], 0
	v_mfma_f32_16x16x32_bf16 v[90:93], v[2:5], v[58:61], 0
	v_mfma_f32_16x16x32_bf16 v[94:97], v[10:13], v[58:61], 0
	v_mfma_f32_16x16x32_bf16 v[66:69], v[6:9], v[38:41], v[66:69]
	v_mfma_f32_16x16x32_bf16 v[70:73], v[14:17], v[38:41], v[70:73]
	v_mfma_f32_16x16x32_bf16 v[74:77], v[6:9], v[46:49], v[74:77]
	v_mfma_f32_16x16x32_bf16 v[78:81], v[14:17], v[46:49], v[78:81]
	v_mfma_f32_16x16x32_bf16 v[82:85], v[6:9], v[54:57], v[82:85]
	v_mfma_f32_16x16x32_bf16 v[86:89], v[14:17], v[54:57], v[86:89]
	v_mfma_f32_16x16x32_bf16 v[90:93], v[6:9], v[62:65], v[90:93]
	v_mfma_f32_16x16x32_bf16 v[94:97], v[14:17], v[62:65], v[94:97]
	v_mfma_f32_16x16x32_bf16 v[98:101], v[18:21], v[34:37], 0
	v_mfma_f32_16x16x32_bf16 v[34:37], v[26:29], v[34:37], 0
	v_mfma_f32_16x16x32_bf16 v[102:105], v[18:21], v[42:45], 0
	v_mfma_f32_16x16x32_bf16 v[42:45], v[26:29], v[42:45], 0
	v_mfma_f32_16x16x32_bf16 v[106:109], v[18:21], v[50:53], 0
	v_mfma_f32_16x16x32_bf16 v[50:53], v[26:29], v[50:53], 0
	v_mfma_f32_16x16x32_bf16 v[110:113], v[18:21], v[58:61], 0
	v_mfma_f32_16x16x32_bf16 v[58:61], v[26:29], v[58:61], 0
	v_mfma_f32_16x16x32_bf16 v[118:121], v[22:25], v[38:41], v[98:101]
	v_mfma_f32_16x16x32_bf16 v[34:37], v[30:33], v[38:41], v[34:37]
	v_mfma_f32_16x16x32_bf16 v[38:41], v[22:25], v[46:49], v[102:105]
	v_mfma_f32_16x16x32_bf16 v[42:45], v[30:33], v[46:49], v[42:45]
	v_mfma_f32_16x16x32_bf16 v[46:49], v[22:25], v[54:57], v[106:109]
	v_mfma_f32_16x16x32_bf16 v[50:53], v[30:33], v[54:57], v[50:53]
	v_mfma_f32_16x16x32_bf16 v[102:105], v[22:25], v[62:65], v[110:113]
	v_mfma_f32_16x16x32_bf16 v[58:61], v[30:33], v[62:65], v[58:61]
	s_barrier
	s_add_i32 s82, s72, s62
	v_mov_b32_e32 v234, v135
	s_mov_b32 m0, s82
	s_add_i32 s83, s82, 0x2000
	ds_read_b128 v[54:57], v143 offset:16384
	ds_read_b128 v[62:65], v143 offset:17408
	ds_read_b128 v[98:101], v143 offset:18432
	ds_read_b128 v[106:109], v143 offset:19456
	ds_read_b128 v[110:113], v143 offset:20480
	ds_read_b128 v[114:117], v143 offset:21504
	ds_read_b128 v[122:125], v143 offset:22528
	ds_read_b128 v[126:129], v143 offset:23552
	v_mov_b32_e32 v235, v137
	global_load_lds_dwordx4 v234, s[8:9]
	s_mov_b32 m0, s83
	s_nop 0
	global_load_lds_dwordx4 v235, s[8:9]
	s_add_u32 s8, s38, 0x40100
	s_addc_u32 s9, s39, 0
	s_add_i32 s34, s73, s62
	s_mov_b32 m0, s34
	s_add_i32 s35, s34, 0x2000
	s_nop 0
	global_load_lds_dwordx4 v234, s[8:9]
	s_mov_b32 m0, s35
	s_nop 0
	global_load_lds_dwordx4 v235, s[8:9]
	s_mov_b64 s[8:9], s[40:41]
	s_mov_b32 m0, s31
	s_nop 0
	global_load_lds_dwordx4 v232, s[8:9]
	s_mov_b32 m0, s65
	s_nop 0
	global_load_lds_dwordx4 v233, s[8:9]
	s_waitcnt vmcnt(8)
	s_waitcnt lgkmcnt(0)
	s_barrier
	s_waitcnt lgkmcnt(0)
	v_mfma_f32_16x16x32_bf16 v[144:147], v[2:5], v[54:57], 0
	v_mfma_f32_16x16x32_bf16 v[148:151], v[10:13], v[54:57], 0
	v_mfma_f32_16x16x32_bf16 v[152:155], v[2:5], v[98:101], 0
	v_mfma_f32_16x16x32_bf16 v[156:159], v[10:13], v[98:101], 0
	v_mfma_f32_16x16x32_bf16 v[160:163], v[2:5], v[110:113], 0
	v_mfma_f32_16x16x32_bf16 v[164:167], v[10:13], v[110:113], 0
	v_mfma_f32_16x16x32_bf16 v[2:5], v[2:5], v[122:125], 0
	v_mfma_f32_16x16x32_bf16 v[10:13], v[10:13], v[122:125], 0
	v_mfma_f32_16x16x32_bf16 v[168:171], v[6:9], v[62:65], v[144:147]
	v_mfma_f32_16x16x32_bf16 v[146:149], v[14:17], v[62:65], v[148:151]
	v_mfma_f32_16x16x32_bf16 v[150:153], v[6:9], v[106:109], v[152:155]
	v_mfma_f32_16x16x32_bf16 v[154:157], v[14:17], v[106:109], v[156:159]
	v_mfma_f32_16x16x32_bf16 v[158:161], v[6:9], v[114:117], v[160:163]
	v_mfma_f32_16x16x32_bf16 v[2:5], v[6:9], v[126:129], v[2:5]
	v_mfma_f32_16x16x32_bf16 v[6:9], v[14:17], v[126:129], v[10:13]
	v_mfma_f32_16x16x32_bf16 v[162:165], v[14:17], v[114:117], v[164:167]
	v_mfma_f32_16x16x32_bf16 v[10:13], v[18:21], v[54:57], 0
	v_mfma_f32_16x16x32_bf16 v[14:17], v[26:29], v[54:57], 0
	v_mfma_f32_16x16x32_bf16 v[54:57], v[18:21], v[98:101], 0
	v_mfma_f32_16x16x32_bf16 v[98:101], v[26:29], v[98:101], 0
	v_mfma_f32_16x16x32_bf16 v[172:175], v[18:21], v[110:113], 0
	v_mfma_f32_16x16x32_bf16 v[110:113], v[26:29], v[110:113], 0
	v_mfma_f32_16x16x32_bf16 v[18:21], v[18:21], v[122:125], 0
	v_mfma_f32_16x16x32_bf16 v[26:29], v[26:29], v[122:125], 0
	v_mfma_f32_16x16x32_bf16 v[176:179], v[22:25], v[62:65], v[10:13]
	v_mfma_f32_16x16x32_bf16 v[14:17], v[30:33], v[62:65], v[14:17]
	v_mfma_f32_16x16x32_bf16 v[180:183], v[22:25], v[106:109], v[54:57]
	v_mfma_f32_16x16x32_bf16 v[184:187], v[30:33], v[106:109], v[98:101]
	v_mfma_f32_16x16x32_bf16 v[172:175], v[22:25], v[114:117], v[172:175]
	v_mfma_f32_16x16x32_bf16 v[188:191], v[30:33], v[114:117], v[110:113]
	v_mfma_f32_16x16x32_bf16 v[22:25], v[22:25], v[126:129], v[18:21]
	v_mfma_f32_16x16x32_bf16 v[30:33], v[30:33], v[126:129], v[26:29]
	s_barrier
	s_add_i32 s11, 0, 0x18000
	s_add_i32 s24, 0, 0x1c000
	v_add_u32_e32 v144, s11, v138
	v_add_u32_e32 v145, s24, v138
	ds_read_b128 v[10:13], v144
	ds_read_b128 v[192:195], v144 offset:1024
	ds_read_b128 v[18:21], v144 offset:2048
	ds_read_b128 v[196:199], v144 offset:3072
	ds_read_b128 v[200:203], v145
	ds_read_b128 v[204:207], v145 offset:1024
	ds_read_b128 v[208:211], v145 offset:2048
	ds_read_b128 v[212:215], v145 offset:3072
	s_add_u32 s8, s42, 0x40100
	s_addc_u32 s9, s43, 0
	s_mov_b32 m0, s66
	ds_read_b128 v[26:29], v143 offset:32768
	ds_read_b128 v[62:65], v143 offset:33792
	ds_read_b128 v[110:113], v143 offset:34816
	ds_read_b128 v[216:219], v143 offset:35840
	ds_read_b128 v[126:129], v143 offset:36864
	ds_read_b128 v[220:223], v143 offset:37888
	ds_read_b128 v[224:227], v143 offset:38912
	ds_read_b128 v[228:231], v143 offset:39936
	s_nop 0
	global_load_lds_dwordx4 v232, s[8:9]
	s_mov_b32 m0, s67
	s_nop 0
	global_load_lds_dwordx4 v233, s[8:9]
	s_waitcnt vmcnt(8)
	s_waitcnt lgkmcnt(0)
	s_barrier
	s_waitcnt lgkmcnt(0)
	v_mfma_f32_16x16x32_bf16 v[54:57], v[10:13], v[26:29], v[66:69]
	v_mfma_f32_16x16x32_bf16 v[66:69], v[18:21], v[26:29], v[70:73]
	v_mfma_f32_16x16x32_bf16 v[70:73], v[10:13], v[110:113], v[74:77]
	v_mfma_f32_16x16x32_bf16 v[74:77], v[18:21], v[110:113], v[78:81]
	v_mfma_f32_16x16x32_bf16 v[78:81], v[10:13], v[126:129], v[82:85]
	v_mfma_f32_16x16x32_bf16 v[82:85], v[18:21], v[126:129], v[86:89]
	v_mfma_f32_16x16x32_bf16 v[86:89], v[10:13], v[224:227], v[90:93]
	v_mfma_f32_16x16x32_bf16 v[94:97], v[18:21], v[224:227], v[94:97]
	v_mfma_f32_16x16x32_bf16 v[122:125], v[192:195], v[62:65], v[54:57]
	v_mfma_f32_16x16x32_bf16 v[114:117], v[196:199], v[62:65], v[66:69]
	v_mfma_f32_16x16x32_bf16 v[106:109], v[192:195], v[216:219], v[70:73]
	v_mfma_f32_16x16x32_bf16 v[98:101], v[196:199], v[216:219], v[74:77]
	v_mfma_f32_16x16x32_bf16 v[90:93], v[192:195], v[220:223], v[78:81]
	v_mfma_f32_16x16x32_bf16 v[82:85], v[196:199], v[220:223], v[82:85]
	v_mfma_f32_16x16x32_bf16 v[74:77], v[192:195], v[228:231], v[86:89]
	v_mfma_f32_16x16x32_bf16 v[54:57], v[196:199], v[228:231], v[94:97]
	v_mfma_f32_16x16x32_bf16 v[66:69], v[200:203], v[26:29], v[118:121]
	v_mfma_f32_16x16x32_bf16 v[26:29], v[208:211], v[26:29], v[34:37]
	v_mfma_f32_16x16x32_bf16 v[34:37], v[200:203], v[110:113], v[38:41]
	v_mfma_f32_16x16x32_bf16 v[38:41], v[208:211], v[110:113], v[42:45]
	v_mfma_f32_16x16x32_bf16 v[42:45], v[200:203], v[126:129], v[46:49]
	v_mfma_f32_16x16x32_bf16 v[46:49], v[208:211], v[126:129], v[50:53]
	v_mfma_f32_16x16x32_bf16 v[50:53], v[200:203], v[224:227], v[102:105]
	v_mfma_f32_16x16x32_bf16 v[58:61], v[208:211], v[224:227], v[58:61]
	v_mfma_f32_16x16x32_bf16 v[126:129], v[204:207], v[62:65], v[66:69]
	v_mfma_f32_16x16x32_bf16 v[118:121], v[212:215], v[62:65], v[26:29]
	v_mfma_f32_16x16x32_bf16 v[110:113], v[204:207], v[216:219], v[34:37]
	v_mfma_f32_16x16x32_bf16 v[102:105], v[212:215], v[216:219], v[38:41]
	v_mfma_f32_16x16x32_bf16 v[94:97], v[204:207], v[220:223], v[42:45]
	v_mfma_f32_16x16x32_bf16 v[86:89], v[212:215], v[220:223], v[46:49]
	v_mfma_f32_16x16x32_bf16 v[78:81], v[204:207], v[228:231], v[50:53]
	v_mfma_f32_16x16x32_bf16 v[62:65], v[212:215], v[228:231], v[58:61]
	s_barrier
	s_add_i32 s11, s11, s62
	s_add_i32 s84, s11, 0x2000
	s_mov_b32 m0, s11
	s_add_u32 s22, s38, 0x40180
	ds_read_b128 v[38:41], v143 offset:49152
	ds_read_b128 v[46:49], v143 offset:50176
	ds_read_b128 v[58:61], v143 offset:51200
	ds_read_b128 v[216:219], v143 offset:52224
	ds_read_b128 v[70:73], v143 offset:53248
	ds_read_b128 v[220:223], v143 offset:54272
	ds_read_b128 v[224:227], v143 offset:55296
	ds_read_b128 v[228:231], v143 offset:56320
	s_addc_u32 s23, s39, 0
	global_load_lds_dwordx4 v234, s[48:49]
	s_mov_b32 m0, s84
	s_add_i32 s8, s24, s62
	global_load_lds_dwordx4 v235, s[48:49]
	s_mov_b32 m0, s8
	s_add_i32 s9, s8, 0x2000
	s_nop 0
	global_load_lds_dwordx4 v234, s[22:23]
	s_mov_b32 m0, s9
	s_nop 0
	global_load_lds_dwordx4 v235, s[22:23]
	s_mov_b32 m0, s69
	s_nop 0
	global_load_lds_dwordx4 v232, s[44:45]
	s_mov_b32 m0, s70
	s_nop 0
	global_load_lds_dwordx4 v233, s[44:45]
	s_waitcnt vmcnt(8)
	s_waitcnt lgkmcnt(0)
	s_barrier
	s_waitcnt lgkmcnt(0)
	v_mfma_f32_16x16x32_bf16 v[26:29], v[10:13], v[38:41], v[168:171]
	v_mfma_f32_16x16x32_bf16 v[34:37], v[18:21], v[38:41], v[146:149]
	v_mfma_f32_16x16x32_bf16 v[42:45], v[10:13], v[58:61], v[150:153]
	v_mfma_f32_16x16x32_bf16 v[146:149], v[18:21], v[58:61], v[154:157]
	v_mfma_f32_16x16x32_bf16 v[150:153], v[10:13], v[70:73], v[158:161]
	v_mfma_f32_16x16x32_bf16 v[154:157], v[18:21], v[70:73], v[162:165]
	v_mfma_f32_16x16x32_bf16 v[2:5], v[10:13], v[224:227], v[2:5]
	v_mfma_f32_16x16x32_bf16 v[6:9], v[18:21], v[224:227], v[6:9]
	v_mfma_f32_16x16x32_bf16 v[66:69], v[192:195], v[46:49], v[26:29]
	v_mfma_f32_16x16x32_bf16 v[50:53], v[196:199], v[46:49], v[34:37]
	v_mfma_f32_16x16x32_bf16 v[42:45], v[192:195], v[216:219], v[42:45]
	v_mfma_f32_16x16x32_bf16 v[34:37], v[196:199], v[216:219], v[146:149]
	v_mfma_f32_16x16x32_bf16 v[26:29], v[192:195], v[220:223], v[150:153]
	v_mfma_f32_16x16x32_bf16 v[18:21], v[196:199], v[220:223], v[154:157]
	v_mfma_f32_16x16x32_bf16 v[10:13], v[192:195], v[228:231], v[2:5]
	v_mfma_f32_16x16x32_bf16 v[2:5], v[196:199], v[228:231], v[6:9]
	v_mfma_f32_16x16x32_bf16 v[6:9], v[200:203], v[38:41], v[176:179]
	v_mfma_f32_16x16x32_bf16 v[14:17], v[208:211], v[38:41], v[14:17]
	v_mfma_f32_16x16x32_bf16 v[38:41], v[200:203], v[58:61], v[180:183]
	v_mfma_f32_16x16x32_bf16 v[146:149], v[208:211], v[58:61], v[184:187]
	v_mfma_f32_16x16x32_bf16 v[150:153], v[200:203], v[70:73], v[172:175]
	v_mfma_f32_16x16x32_bf16 v[154:157], v[208:211], v[70:73], v[188:191]
	v_mfma_f32_16x16x32_bf16 v[158:161], v[200:203], v[224:227], v[22:25]
	v_mfma_f32_16x16x32_bf16 v[162:165], v[208:211], v[224:227], v[30:33]
	v_mfma_f32_16x16x32_bf16 v[70:73], v[204:207], v[46:49], v[6:9]
	v_mfma_f32_16x16x32_bf16 v[58:61], v[212:215], v[46:49], v[14:17]
	v_mfma_f32_16x16x32_bf16 v[46:49], v[204:207], v[216:219], v[38:41]
	v_mfma_f32_16x16x32_bf16 v[38:41], v[212:215], v[216:219], v[146:149]
	v_mfma_f32_16x16x32_bf16 v[30:33], v[204:207], v[220:223], v[150:153]
	v_mfma_f32_16x16x32_bf16 v[22:25], v[212:215], v[220:223], v[154:157]
	v_mfma_f32_16x16x32_bf16 v[14:17], v[204:207], v[228:231], v[158:161]
	v_mfma_f32_16x16x32_bf16 v[6:9], v[212:215], v[228:231], v[162:165]
	s_barrier
	s_add_u32 s78, s38, 0x200
	s_addc_u32 s85, s39, 0
	s_mov_b32 s22, 0
